# swiglu phases: deferred output stores spread over the whole next K-loop (one store per two K iterations)
# baseline (speedup 1.0000x reference)
; #define PG8_STAGE(bufoff, gbase, voff) do { _Pragma("unroll") for (int _i = 0; _i < 2; ++_i) \
;         __builtin_amdgcn_global_load_lds((const unsigned*)((const char*)(gbase) + (voff)[_i]), (PG8_LAS unsigned*)(lds + (bufoff) + ldsw + _i * 8192), 16, 0, 0); } while (0)
; #define PG8_LDA(dst, b, h) do { _Pragma("unroll") for (int m = 0; m < 4; ++m) _Pragma("unroll") for (int k = 0; k < 2; ++k) dst[m][k] = *(const PG8_LAS bf16x8*)(lds + PG8_SA(b, h) + aoff + m * 2048 + k * 1024); } while (0)
; #define PG8_LDB(dst, b, h) do { _Pragma("unroll") for (int n = 0; n < 2; ++n) _Pragma("unroll") for (int k = 0; k < 2; ++k) dst[n][k] = *(const PG8_LAS bf16x8*)(lds + PG8_SB(b, h) + boff + n * 2048 + k * 1024); } while (0)
; #define PG8_MMA(ai, bj, At, Bt) do { __builtin_amdgcn_s_setprio(1); _Pragma("unroll") for (int m = 0; m < 4; ++m) _Pragma("unroll") for (int n = 0; n < 2; ++n) _Pragma("unroll") for (int k = 0; k < 2; ++k) \
;         acc[ai][bj][m][n] = __builtin_amdgcn_mfma_f32_16x16x32_bf16(Bt[n][k], At[m][k], acc[ai][bj][m][n], 0, 0, 0); __builtin_amdgcn_s_setprio(0); } while (0)
; #define PG8_WAIT_V(n) asm volatile("s_waitcnt vmcnt(" #n ")" ::: "memory")
; #define PG8_WAIT_L(n) asm volatile("s_waitcnt lgkmcnt(" #n ")" ::: "memory")
; #define PG8_BAR __builtin_amdgcn_s_barrier()
; #define PG8_SCHED __builtin_amdgcn_sched_barrier(0)
; template <class Epi, class Sched>
; __device__ __forceinline__ void gemm_phase(PG8_LAS unsigned char* lds, const Gemm g, const Sched& S, const Epi& E) {
;     ...
;             PG8_LDB(B0, 0, 0); PG8_SCHED; PG8_LDA(At, 0, 0); PG8_STAGE(PG8_SA(1, 1), a1 + hstepA, voffA);
;             PG8_WAIT_L(8); PG8_BAR; PG8_WAIT_L(0); PG8_MMA(0, 0, At, B0); PG8_BAR; PG8_SCHED;
;             PG8_LDB(B1, 0, 1); PG8_STAGE(PG8_SB(0, 0), b2, voffB);
;             PG8_BAR; PG8_WAIT_L(0); PG8_MMA(0, 1, At, B1); PG8_BAR;
;             PG8_LDA(At, 0, 1); PG8_STAGE(PG8_SA(0, 0), a2, voffA);
;             PG8_BAR; PG8_WAIT_L(0); PG8_MMA(1, 0, At, B0); PG8_BAR; PG8_SCHED;
;             PG8_STAGE(PG8_SB(0, 1), b2 + hstepB, voffB);
;             PG8_WAIT_V(6); PG8_BAR; PG8_MMA(1, 1, At, B1); PG8_BAR;
.LBB0_482:
	ds_read_b128 v[154:157], v151
	ds_read_b128 v[158:161], v151 offset:1024
	ds_read_b128 v[162:165], v151 offset:2048
	ds_read_b128 v[166:169], v151 offset:3072
	s_add_u32 s26, s24, 0xfff80080
	s_addc_u32 s27, s25, -1
	s_cmp_eq_u32 s55, 28
	s_cselect_b32 s29, s17, s27
	s_cselect_b32 s28, s51, s26
	s_cselect_b32 s27, s15, s54
	s_cselect_b32 s26, s52, s53
	v_lshl_add_u64 v[146:147], s[24:25], 0, v[138:139]
	s_add_i32 m0, s23, 0xc000
	ds_read_b128 v[170:173], v152
	ds_read_b128 v[174:177], v152 offset:1024
	ds_read_b128 v[178:181], v152 offset:2048
	ds_read_b128 v[182:185], v152 offset:3072
	ds_read_b128 v[186:189], v152 offset:4096
	ds_read_b128 v[190:193], v152 offset:5120
	ds_read_b128 v[194:197], v152 offset:6144
	ds_read_b128 v[198:201], v152 offset:7168
	global_load_lds_dwordx4 v[146:147], off
	v_lshl_add_u64 v[146:147], s[24:25], 0, v[140:141]
	s_add_i32 m0, s23, 0xe000
	s_nop 0
	global_load_lds_dwordx4 v[146:147], off
	s_waitcnt lgkmcnt(8)
	s_barrier
	s_waitcnt lgkmcnt(0)
	s_setprio 1
	s_waitcnt lgkmcnt(0)
	v_mfma_f32_16x16x32_bf16 v[126:129], v[154:157], v[170:173], v[126:129]
	v_mfma_f32_16x16x32_bf16 v[122:125], v[162:165], v[170:173], v[122:125]
	v_mfma_f32_16x16x32_bf16 v[110:113], v[154:157], v[178:181], v[110:113]
	v_mfma_f32_16x16x32_bf16 v[106:109], v[162:165], v[178:181], v[106:109]
	v_mfma_f32_16x16x32_bf16 v[94:97], v[154:157], v[186:189], v[94:97]
	v_mfma_f32_16x16x32_bf16 v[90:93], v[162:165], v[186:189], v[90:93]
	v_mfma_f32_16x16x32_bf16 v[78:81], v[154:157], v[194:197], v[78:81]
	v_mfma_f32_16x16x32_bf16 v[74:77], v[162:165], v[194:197], v[74:77]
	v_mfma_f32_16x16x32_bf16 v[126:129], v[158:161], v[174:177], v[126:129]
	v_mfma_f32_16x16x32_bf16 v[122:125], v[166:169], v[174:177], v[122:125]
	v_mfma_f32_16x16x32_bf16 v[110:113], v[158:161], v[182:185], v[110:113]
	v_mfma_f32_16x16x32_bf16 v[106:109], v[166:169], v[182:185], v[106:109]
	v_mfma_f32_16x16x32_bf16 v[94:97], v[158:161], v[190:193], v[94:97]
	v_mfma_f32_16x16x32_bf16 v[90:93], v[166:169], v[190:193], v[90:93]
	v_mfma_f32_16x16x32_bf16 v[78:81], v[158:161], v[198:201], v[78:81]
	v_mfma_f32_16x16x32_bf16 v[74:77], v[166:169], v[198:201], v[74:77]
	s_setprio 0
	s_barrier
	s_add_i32 s56, s47, s36
	v_lshl_add_u64 v[146:147], s[26:27], 0, v[132:133]
	s_mov_b32 m0, s56
	ds_read_b128 v[202:205], v153
	ds_read_b128 v[206:209], v153 offset:1024
	ds_read_b128 v[210:213], v153 offset:2048
	ds_read_b128 v[214:217], v153 offset:3072
	global_load_lds_dwordx4 v[146:147], off
	v_lshl_add_u64 v[218:219], s[26:27], 0, v[136:137]
	s_add_i32 m0, s56, 0x2000
	s_nop 0
	global_load_lds_dwordx4 v[218:219], off
	s_barrier
	s_waitcnt lgkmcnt(0)
	s_setprio 1
	s_waitcnt lgkmcnt(0)
	v_mfma_f32_16x16x32_bf16 v[118:121], v[202:205], v[170:173], v[118:121]
	v_mfma_f32_16x16x32_bf16 v[114:117], v[210:213], v[170:173], v[114:117]
	v_mfma_f32_16x16x32_bf16 v[102:105], v[202:205], v[178:181], v[102:105]
	v_mfma_f32_16x16x32_bf16 v[98:101], v[210:213], v[178:181], v[98:101]
	v_mfma_f32_16x16x32_bf16 v[86:89], v[202:205], v[186:189], v[86:89]
	v_mfma_f32_16x16x32_bf16 v[82:85], v[210:213], v[186:189], v[82:85]
	v_mfma_f32_16x16x32_bf16 v[70:73], v[202:205], v[194:197], v[70:73]
	v_mfma_f32_16x16x32_bf16 v[66:69], v[210:213], v[194:197], v[66:69]
	v_mfma_f32_16x16x32_bf16 v[118:121], v[206:209], v[174:177], v[118:121]
	v_mfma_f32_16x16x32_bf16 v[114:117], v[214:217], v[174:177], v[114:117]
	v_mfma_f32_16x16x32_bf16 v[102:105], v[206:209], v[182:185], v[102:105]
	v_mfma_f32_16x16x32_bf16 v[98:101], v[214:217], v[182:185], v[98:101]
	v_mfma_f32_16x16x32_bf16 v[86:89], v[206:209], v[190:193], v[86:89]
	v_mfma_f32_16x16x32_bf16 v[82:85], v[214:217], v[190:193], v[82:85]
	v_mfma_f32_16x16x32_bf16 v[70:73], v[206:209], v[198:201], v[70:73]
	v_mfma_f32_16x16x32_bf16 v[66:69], v[214:217], v[198:201], v[66:69]
	s_setprio 0
	s_mov_b32 m0, s23
	v_lshl_add_u64 v[220:221], s[28:29], 0, v[130:131]
	s_barrier
	ds_read_b128 v[170:173], v152 offset:16384
	ds_read_b128 v[174:177], v152 offset:17408
	ds_read_b128 v[178:181], v152 offset:18432
	ds_read_b128 v[182:185], v152 offset:19456
	ds_read_b128 v[186:189], v152 offset:20480
	ds_read_b128 v[190:193], v152 offset:21504
	ds_read_b128 v[194:197], v152 offset:22528
	ds_read_b128 v[198:201], v152 offset:23552
	global_load_lds_dwordx4 v[220:221], off
	v_lshl_add_u64 v[222:223], s[28:29], 0, v[134:135]
	s_mov_b32 m0, s39
	s_nop 0
	global_load_lds_dwordx4 v[222:223], off
	s_barrier
	s_waitcnt lgkmcnt(0)
	s_setprio 1
	s_waitcnt lgkmcnt(0)
	v_mfma_f32_16x16x32_bf16 v[62:65], v[154:157], v[170:173], v[62:65]
	v_mfma_f32_16x16x32_bf16 v[58:61], v[162:165], v[170:173], v[58:61]
	v_mfma_f32_16x16x32_bf16 v[46:49], v[154:157], v[178:181], v[46:49]
	v_mfma_f32_16x16x32_bf16 v[42:45], v[162:165], v[178:181], v[42:45]
	v_mfma_f32_16x16x32_bf16 v[30:33], v[154:157], v[186:189], v[30:33]
	v_mfma_f32_16x16x32_bf16 v[26:29], v[162:165], v[186:189], v[26:29]
	v_mfma_f32_16x16x32_bf16 v[14:17], v[154:157], v[194:197], v[14:17]
	v_mfma_f32_16x16x32_bf16 v[10:13], v[162:165], v[194:197], v[10:13]
	v_mfma_f32_16x16x32_bf16 v[62:65], v[158:161], v[174:177], v[62:65]
	v_mfma_f32_16x16x32_bf16 v[58:61], v[166:169], v[174:177], v[58:61]
	v_mfma_f32_16x16x32_bf16 v[46:49], v[158:161], v[182:185], v[46:49]
	v_mfma_f32_16x16x32_bf16 v[42:45], v[166:169], v[182:185], v[42:45]
	v_mfma_f32_16x16x32_bf16 v[30:33], v[158:161], v[190:193], v[30:33]
	v_mfma_f32_16x16x32_bf16 v[26:29], v[166:169], v[190:193], v[26:29]
	v_mfma_f32_16x16x32_bf16 v[14:17], v[158:161], v[198:201], v[14:17]
	v_mfma_f32_16x16x32_bf16 v[10:13], v[166:169], v[198:201], v[10:13]
	s_setprio 0
	s_barrier
; #define PG8_STAGE(bufoff, gbase, voff) do { _Pragma("unroll") for (int _i = 0; _i < 2; ++_i) \
;         __builtin_amdgcn_global_load_lds((const unsigned*)((const char*)(gbase) + (voff)[_i]), (PG8_LAS unsigned*)(lds + (bufoff) + ldsw + _i * 8192), 16, 0, 0); } while (0)
; #define PG8_LDA(dst, b, h) do { _Pragma("unroll") for (int m = 0; m < 4; ++m) _Pragma("unroll") for (int k = 0; k < 2; ++k) dst[m][k] = *(const PG8_LAS bf16x8*)(lds + PG8_SA(b, h) + aoff + m * 2048 + k * 1024); } while (0)
; #define PG8_LDB(dst, b, h) do { _Pragma("unroll") for (int n = 0; n < 2; ++n) _Pragma("unroll") for (int k = 0; k < 2; ++k) dst[n][k] = *(const PG8_LAS bf16x8*)(lds + PG8_SB(b, h) + boff + n * 2048 + k * 1024); } while (0)
; #define PG8_MMA(ai, bj, At, Bt) do { __builtin_amdgcn_s_setprio(1); _Pragma("unroll") for (int m = 0; m < 4; ++m) _Pragma("unroll") for (int n = 0; n < 2; ++n) _Pragma("unroll") for (int k = 0; k < 2; ++k) \
;         acc[ai][bj][m][n] = __builtin_amdgcn_mfma_f32_16x16x32_bf16(Bt[n][k], At[m][k], acc[ai][bj][m][n], 0, 0, 0); __builtin_amdgcn_s_setprio(0); } while (0)
; #define PG8_WAIT_V(n) asm volatile("s_waitcnt vmcnt(" #n ")" ::: "memory")
; #define PG8_WAIT_L(n) asm volatile("s_waitcnt lgkmcnt(" #n ")" ::: "memory")
; #define PG8_BAR __builtin_amdgcn_s_barrier()
; #define PG8_SCHED __builtin_amdgcn_sched_barrier(0)
; template <class Epi, class Sched>
; __device__ __forceinline__ void gemm_phase(PG8_LAS unsigned char* lds, const Gemm g, const Sched& S, const Epi& E) {
;     ...
;             PG8_WAIT_V(6); PG8_BAR; PG8_MMA(1, 1, At, B1); PG8_BAR;
;             PG8_LDB(B0, 1, 0); PG8_SCHED; PG8_LDA(At, 1, 0); PG8_STAGE(PG8_SA(0, 1), a2 + hstepA, voffA);
;             PG8_WAIT_L(8); PG8_BAR; PG8_WAIT_L(0); PG8_MMA(0, 0, At, B0); PG8_BAR; PG8_SCHED;
;             PG8_LDB(B1, 1, 1); PG8_STAGE(PG8_SB(1, 0), b3, voffB);
;             PG8_BAR; PG8_WAIT_L(0); PG8_MMA(0, 1, At, B1); PG8_BAR;
	s_add_u32 s56, s26, 0x80000
	s_addc_u32 s57, s27, 0
	s_add_i32 s58, s48, s36
	v_lshl_add_u64 v[154:155], s[56:57], 0, v[132:133]
	s_mov_b32 m0, s58
	s_nop 0
	global_load_lds_dwordx4 v[154:155], off
	v_lshl_add_u64 v[154:155], s[56:57], 0, v[136:137]
	s_add_i32 m0, s58, 0x2000
	s_nop 0
	global_load_lds_dwordx4 v[154:155], off
	s_waitcnt vmcnt(6)
	s_barrier
	s_setprio 1
	v_mfma_f32_16x16x32_bf16 v[54:57], v[202:205], v[170:173], v[54:57]
	v_mfma_f32_16x16x32_bf16 v[50:53], v[210:213], v[170:173], v[50:53]
	v_mfma_f32_16x16x32_bf16 v[38:41], v[202:205], v[178:181], v[38:41]
	v_mfma_f32_16x16x32_bf16 v[34:37], v[210:213], v[178:181], v[34:37]
	v_mfma_f32_16x16x32_bf16 v[22:25], v[202:205], v[186:189], v[22:25]
	v_mfma_f32_16x16x32_bf16 v[18:21], v[210:213], v[186:189], v[18:21]
	v_mfma_f32_16x16x32_bf16 v[6:9], v[202:205], v[194:197], v[6:9]
	v_mfma_f32_16x16x32_bf16 v[2:5], v[210:213], v[194:197], v[2:5]
	v_mfma_f32_16x16x32_bf16 v[54:57], v[206:209], v[174:177], v[54:57]
	v_mfma_f32_16x16x32_bf16 v[50:53], v[214:217], v[174:177], v[50:53]
	v_mfma_f32_16x16x32_bf16 v[38:41], v[206:209], v[182:185], v[38:41]
	v_mfma_f32_16x16x32_bf16 v[34:37], v[214:217], v[182:185], v[34:37]
	v_mfma_f32_16x16x32_bf16 v[22:25], v[206:209], v[190:193], v[22:25]
	v_mfma_f32_16x16x32_bf16 v[18:21], v[214:217], v[190:193], v[18:21]
	v_mfma_f32_16x16x32_bf16 v[6:9], v[206:209], v[198:201], v[6:9]
	v_mfma_f32_16x16x32_bf16 v[2:5], v[214:217], v[198:201], v[2:5]
	s_setprio 0
	s_add_i32 s56, 0, 0x18000
	v_add_u32_e32 v166, s56, v149
	s_barrier
	ds_read_b128 v[154:157], v166
	ds_read_b128 v[158:161], v166 offset:1024
	ds_read_b128 v[162:165], v166 offset:2048
	ds_read_b128 v[166:169], v166 offset:3072
	s_add_u32 s28, s28, 0x80000
	s_addc_u32 s29, s29, 0
	s_mov_b32 m0, s40
	v_lshl_add_u64 v[202:203], s[28:29], 0, v[130:131]
	ds_read_b128 v[170:173], v152 offset:32768
	ds_read_b128 v[174:177], v152 offset:33792
	ds_read_b128 v[178:181], v152 offset:34816
	ds_read_b128 v[182:185], v152 offset:35840
	ds_read_b128 v[186:189], v152 offset:36864
	ds_read_b128 v[190:193], v152 offset:37888
	ds_read_b128 v[194:197], v152 offset:38912
	ds_read_b128 v[198:201], v152 offset:39936
	global_load_lds_dwordx4 v[202:203], off
	v_lshl_add_u64 v[202:203], s[28:29], 0, v[134:135]
	s_mov_b32 m0, s41
	s_nop 0
	global_load_lds_dwordx4 v[202:203], off
	s_waitcnt lgkmcnt(8)
	s_barrier
	s_waitcnt lgkmcnt(0)
	s_setprio 1
	s_waitcnt lgkmcnt(0)
	v_mfma_f32_16x16x32_bf16 v[126:129], v[154:157], v[170:173], v[126:129]
	v_mfma_f32_16x16x32_bf16 v[122:125], v[162:165], v[170:173], v[122:125]
	v_mfma_f32_16x16x32_bf16 v[110:113], v[154:157], v[178:181], v[110:113]
	v_mfma_f32_16x16x32_bf16 v[106:109], v[162:165], v[178:181], v[106:109]
	v_mfma_f32_16x16x32_bf16 v[94:97], v[154:157], v[186:189], v[94:97]
	v_mfma_f32_16x16x32_bf16 v[90:93], v[162:165], v[186:189], v[90:93]
	v_mfma_f32_16x16x32_bf16 v[78:81], v[154:157], v[194:197], v[78:81]
	v_mfma_f32_16x16x32_bf16 v[74:77], v[162:165], v[194:197], v[74:77]
	v_mfma_f32_16x16x32_bf16 v[126:129], v[158:161], v[174:177], v[126:129]
	v_mfma_f32_16x16x32_bf16 v[122:125], v[166:169], v[174:177], v[122:125]
	v_mfma_f32_16x16x32_bf16 v[110:113], v[158:161], v[182:185], v[110:113]
	v_mfma_f32_16x16x32_bf16 v[106:109], v[166:169], v[182:185], v[106:109]
	v_mfma_f32_16x16x32_bf16 v[94:97], v[158:161], v[190:193], v[94:97]
	v_mfma_f32_16x16x32_bf16 v[90:93], v[166:169], v[190:193], v[90:93]
	v_mfma_f32_16x16x32_bf16 v[78:81], v[158:161], v[198:201], v[78:81]
	v_mfma_f32_16x16x32_bf16 v[74:77], v[166:169], v[198:201], v[74:77]
	s_setprio 0
	s_barrier
	s_add_i32 s28, 0, 0x1c000
	s_add_i32 s29, s56, s36
	v_add_u32_e32 v214, s28, v149
	v_lshl_add_u64 v[146:147], v[146:147], 0, s[12:13]
	s_mov_b32 m0, s29
	ds_read_b128 v[202:205], v214
	ds_read_b128 v[206:209], v214 offset:1024
	ds_read_b128 v[210:213], v214 offset:2048
	ds_read_b128 v[214:217], v214 offset:3072
	global_load_lds_dwordx4 v[146:147], off
	v_lshl_add_u64 v[146:147], v[218:219], 0, s[12:13]
	s_add_i32 m0, s29, 0x2000
	s_nop 0
	global_load_lds_dwordx4 v[146:147], off
	s_barrier
; #define PG8_STAGE(bufoff, gbase, voff) do { _Pragma("unroll") for (int _i = 0; _i < 2; ++_i) \
;         __builtin_amdgcn_global_load_lds((const unsigned*)((const char*)(gbase) + (voff)[_i]), (PG8_LAS unsigned*)(lds + (bufoff) + ldsw + _i * 8192), 16, 0, 0); } while (0)
; #define PG8_LDA(dst, b, h) do { _Pragma("unroll") for (int m = 0; m < 4; ++m) _Pragma("unroll") for (int k = 0; k < 2; ++k) dst[m][k] = *(const PG8_LAS bf16x8*)(lds + PG8_SA(b, h) + aoff + m * 2048 + k * 1024); } while (0)
; #define PG8_MMA(ai, bj, At, Bt) do { __builtin_amdgcn_s_setprio(1); _Pragma("unroll") for (int m = 0; m < 4; ++m) _Pragma("unroll") for (int n = 0; n < 2; ++n) _Pragma("unroll") for (int k = 0; k < 2; ++k) \
;         acc[ai][bj][m][n] = __builtin_amdgcn_mfma_f32_16x16x32_bf16(Bt[n][k], At[m][k], acc[ai][bj][m][n], 0, 0, 0); __builtin_amdgcn_s_setprio(0); } while (0)
; #define PG8_WAIT_V(n) asm volatile("s_waitcnt vmcnt(" #n ")" ::: "memory")
; #define PG8_WAIT_L(n) asm volatile("s_waitcnt lgkmcnt(" #n ")" ::: "memory")
; #define PG8_BAR __builtin_amdgcn_s_barrier()
; #define PG8_SCHED __builtin_amdgcn_sched_barrier(0)
; template <class Epi, class Sched>
; __device__ __forceinline__ void gemm_phase(PG8_LAS unsigned char* lds, const Gemm g, const Sched& S, const Epi& E) {
;     ...
;             PG8_BAR; PG8_WAIT_L(0); PG8_MMA(0, 1, At, B1); PG8_BAR;
;             PG8_LDA(At, 1, 1); PG8_STAGE(PG8_SA(1, 0), a3, voffA);
;             PG8_BAR; PG8_WAIT_L(0); PG8_MMA(1, 0, At, B0); PG8_BAR; PG8_SCHED;
;             PG8_STAGE(PG8_SB(1, 1), b3 + hstepB, voffB);
;             PG8_WAIT_V(6); PG8_BAR; PG8_MMA(1, 1, At, B1); PG8_BAR;
	s_waitcnt lgkmcnt(0)
	s_setprio 1
	s_waitcnt lgkmcnt(0)
	v_mfma_f32_16x16x32_bf16 v[118:121], v[202:205], v[170:173], v[118:121]
	v_mfma_f32_16x16x32_bf16 v[114:117], v[210:213], v[170:173], v[114:117]
	v_mfma_f32_16x16x32_bf16 v[102:105], v[202:205], v[178:181], v[102:105]
	v_mfma_f32_16x16x32_bf16 v[98:101], v[210:213], v[178:181], v[98:101]
	v_mfma_f32_16x16x32_bf16 v[86:89], v[202:205], v[186:189], v[86:89]
	v_mfma_f32_16x16x32_bf16 v[82:85], v[210:213], v[186:189], v[82:85]
	v_mfma_f32_16x16x32_bf16 v[70:73], v[202:205], v[194:197], v[70:73]
	v_mfma_f32_16x16x32_bf16 v[66:69], v[210:213], v[194:197], v[66:69]
	v_mfma_f32_16x16x32_bf16 v[118:121], v[206:209], v[174:177], v[118:121]
	v_mfma_f32_16x16x32_bf16 v[114:117], v[214:217], v[174:177], v[114:117]
	v_mfma_f32_16x16x32_bf16 v[102:105], v[206:209], v[182:185], v[102:105]
	v_mfma_f32_16x16x32_bf16 v[98:101], v[214:217], v[182:185], v[98:101]
	v_mfma_f32_16x16x32_bf16 v[86:89], v[206:209], v[190:193], v[86:89]
	v_mfma_f32_16x16x32_bf16 v[82:85], v[214:217], v[190:193], v[82:85]
	v_mfma_f32_16x16x32_bf16 v[70:73], v[206:209], v[198:201], v[70:73]
	v_mfma_f32_16x16x32_bf16 v[66:69], v[214:217], v[198:201], v[66:69]
	s_setprio 0
	s_mov_b32 m0, s44
	v_lshl_add_u64 v[146:147], v[220:221], 0, s[12:13]
	s_barrier
	ds_read_b128 v[170:173], v152 offset:49152
	ds_read_b128 v[174:177], v152 offset:50176
	ds_read_b128 v[178:181], v152 offset:51200
	ds_read_b128 v[182:185], v152 offset:52224
	ds_read_b128 v[186:189], v152 offset:53248
	ds_read_b128 v[190:193], v152 offset:54272
	ds_read_b128 v[194:197], v152 offset:55296
	ds_read_b128 v[198:201], v152 offset:56320
	global_load_lds_dwordx4 v[146:147], off
	v_lshl_add_u64 v[146:147], v[222:223], 0, s[12:13]
	s_mov_b32 m0, s45
	s_nop 0
	global_load_lds_dwordx4 v[146:147], off
	s_barrier
	s_waitcnt lgkmcnt(0)
	s_setprio 1
	s_waitcnt lgkmcnt(0)
	v_mfma_f32_16x16x32_bf16 v[62:65], v[154:157], v[170:173], v[62:65]
	v_mfma_f32_16x16x32_bf16 v[58:61], v[162:165], v[170:173], v[58:61]
	v_mfma_f32_16x16x32_bf16 v[46:49], v[154:157], v[178:181], v[46:49]
	v_mfma_f32_16x16x32_bf16 v[42:45], v[162:165], v[178:181], v[42:45]
	v_mfma_f32_16x16x32_bf16 v[30:33], v[154:157], v[186:189], v[30:33]
	v_mfma_f32_16x16x32_bf16 v[26:29], v[162:165], v[186:189], v[26:29]
	v_mfma_f32_16x16x32_bf16 v[14:17], v[154:157], v[194:197], v[14:17]
	v_mfma_f32_16x16x32_bf16 v[10:13], v[162:165], v[194:197], v[10:13]
	v_mfma_f32_16x16x32_bf16 v[62:65], v[158:161], v[174:177], v[62:65]
	v_mfma_f32_16x16x32_bf16 v[58:61], v[166:169], v[174:177], v[58:61]
	v_mfma_f32_16x16x32_bf16 v[46:49], v[158:161], v[182:185], v[46:49]
	v_mfma_f32_16x16x32_bf16 v[42:45], v[166:169], v[182:185], v[42:45]
	v_mfma_f32_16x16x32_bf16 v[30:33], v[158:161], v[190:193], v[30:33]
	v_mfma_f32_16x16x32_bf16 v[26:29], v[166:169], v[190:193], v[26:29]
	v_mfma_f32_16x16x32_bf16 v[14:17], v[158:161], v[198:201], v[14:17]
	v_mfma_f32_16x16x32_bf16 v[10:13], v[166:169], v[198:201], v[10:13]
	s_setprio 0
	s_barrier
	s_add_u32 s26, s26, 0x80080
	s_addc_u32 s27, s27, 0
	s_add_i32 s28, s28, s36
	v_lshl_add_u64 v[146:147], s[26:27], 0, v[132:133]
	s_mov_b32 m0, s28
	s_nop 0
	global_load_lds_dwordx4 v[146:147], off
	v_lshl_add_u64 v[146:147], s[26:27], 0, v[136:137]
	s_add_i32 m0, s28, 0x2000
	s_nop 0
	global_load_lds_dwordx4 v[146:147], off
	s_waitcnt vmcnt(6)
	s_cmp_eq_u64 s[98:99], 0
	s_cbranch_scc1 .Ltk482_8d
	s_and_b32 s100, s55, 3
	s_cmp_lg_u32 s100, 0
	s_cbranch_scc1 .Ltk482_8d
	s_cmp_gt_i32 s55, 24
	s_cbranch_scc1 .Ltk482_8d
	s_cmp_eq_u32 s55, 0
	s_cbranch_scc1 .Ltk482_k1
	s_cmp_eq_u32 s55, 4
	s_cbranch_scc1 .Ltk482_k2
	s_cmp_eq_u32 s55, 8
	s_cbranch_scc1 .Ltk482_k3
	s_cmp_eq_u32 s55, 12
	s_cbranch_scc1 .Ltk482_k4
	s_cmp_eq_u32 s55, 16
	s_cbranch_scc1 .Ltk482_k5
	s_cmp_eq_u32 s55, 20
	s_cbranch_scc1 .Ltk482_k6
	s_add_u32 s100, s98, 0x1e4000
	s_addc_u32 s101, s99, 0
	global_store_dwordx4 v252, v[248:251], s[100:101]
	s_branch .Ltk482_8d
.Ltk482_k1:
	s_add_u32 s100, s98, 0x2c000
	s_addc_u32 s101, s99, 0
	global_store_dwordx4 v252, v[224:227], s[100:101]
	s_branch .Ltk482_8d
.Ltk482_k2:
	s_add_u32 s100, s98, 0x58000
	s_addc_u32 s101, s99, 0
	global_store_dwordx4 v252, v[228:231], s[100:101]
	s_branch .Ltk482_8d
.Ltk482_k3:
	s_add_u32 s100, s98, 0x84000
	s_addc_u32 s101, s99, 0
	global_store_dwordx4 v252, v[232:235], s[100:101]
	s_branch .Ltk482_8d
.Ltk482_k4:
	s_add_u32 s100, s98, 0x160000
	s_addc_u32 s101, s99, 0
	global_store_dwordx4 v252, v[236:239], s[100:101]
	s_branch .Ltk482_8d
.Ltk482_k5:
	s_add_u32 s100, s98, 0x18c000
	s_addc_u32 s101, s99, 0
	global_store_dwordx4 v252, v[240:243], s[100:101]
	s_branch .Ltk482_8d
.Ltk482_k6:
	s_add_u32 s100, s98, 0x1b8000
	s_addc_u32 s101, s99, 0
	global_store_dwordx4 v252, v[244:247], s[100:101]

; #define PG8_STAGE(bufoff, gbase, voff) do { _Pragma("unroll") for (int _i = 0; _i < 2; ++_i) \
;         __builtin_amdgcn_global_load_lds((const unsigned*)((const char*)(gbase) + (voff)[_i]), (PG8_LAS unsigned*)(lds + (bufoff) + ldsw + _i * 8192), 16, 0, 0); } while (0)
; #define PG8_MMA(ai, bj, At, Bt) do { __builtin_amdgcn_s_setprio(1); _Pragma("unroll") for (int m = 0; m < 4; ++m) _Pragma("unroll") for (int n = 0; n < 2; ++n) _Pragma("unroll") for (int k = 0; k < 2; ++k) \
;         acc[ai][bj][m][n] = __builtin_amdgcn_mfma_f32_16x16x32_bf16(Bt[n][k], At[m][k], acc[ai][bj][m][n], 0, 0, 0); __builtin_amdgcn_s_setprio(0); } while (0)
; #define PG8_WAIT_V(n) asm volatile("s_waitcnt vmcnt(" #n ")" ::: "memory")
; #define PG8_BAR __builtin_amdgcn_s_barrier()
; template <class Epi, class Sched>
; __device__ __forceinline__ void gemm_phase(PG8_LAS unsigned char* lds, const Gemm g, const Sched& S, const Epi& E) {
;     ...
;             PG8_STAGE(PG8_SB(1, 1), b3 + hstepB, voffB);
;             PG8_WAIT_V(6); PG8_BAR; PG8_MMA(1, 1, At, B1); PG8_BAR;
.Ltk1179_k1:
	s_add_u32 s100, s98, 0x2c000
	s_addc_u32 s101, s99, 0
	global_store_dwordx4 v252, v[224:227], s[100:101]
	s_branch .Ltk1179_8d
.Ltk1179_k2:
	s_add_u32 s100, s98, 0x58000
	s_addc_u32 s101, s99, 0
	global_store_dwordx4 v252, v[228:231], s[100:101]
	s_branch .Ltk1179_8d
.Ltk1179_k3:
	s_add_u32 s100, s98, 0x84000
	s_addc_u32 s101, s99, 0
	global_store_dwordx4 v252, v[232:235], s[100:101]
	s_branch .Ltk1179_8d
